# skip XCD-leader L2 writeback at 3 panel-local seams (after branch, out-proj, FFN2 gate-up); guarded by a runtime check that all WGs with equal blockIdx%8 share one hardware XCC
# speedup vs baseline: 1.0095x; 1.0095x over previous
.LBB0_179:
	s_add_u32 s0, s86, 0x100000
	s_addc_u32 s1, s87, 0
	v_writelane_b32 v252, s0, 1
	s_mov_b32 s2, 0
	v_cmp_eq_u32_e64 s[92:93], 0, v206
	v_writelane_b32 v252, s1, 2
	s_getreg_b32 s0, hwreg(HW_REG_XCC_ID, 0, 4)
	s_and_b32 s79, s0, 15
	s_and_saveexec_b64 s[0:1], s[92:93]
	s_cbranch_execz .LBB0_182
	s_mov_b64 s[4:5], exec
	v_mbcnt_lo_u32_b32 v0, s4, 0
	v_mbcnt_hi_u32_b32 v0, s5, v0
	v_cmp_eq_u32_e32 vcc, 0, v0
	s_and_b64 s[6:7], exec, vcc
	s_mov_b64 exec, s[6:7]
	s_cbranch_execz .LBB0_182
	s_bcnt1_i32_b64 s4, s[4:5]
	s_lshl_b32 s3, s79, 8
	v_mov_b32_e32 v1, s4
	v_readlane_b32 s4, v252, 1
	v_mov_b32_e32 v0, s3
	v_readlane_b32 s5, v252, 2
	s_nop 4
	s_and_b32 s6, s78, 7
	s_lshl_b32 s6, s6, 2
	s_lshl_b32 s7, 1, s79
	v_mov_b32_e32 v2, s6
	v_mov_b32_e32 v4, s7
	global_atomic_or v2, v4, s[4:5]
	global_atomic_add v0, v1, s[4:5] offset:1024

.LBB0_234:
	s_or_b64 exec, exec, s[0:1]
	s_cmpk_lt_i32 s78, 0xb0
	s_cselect_b64 s[0:1], -1, 0
	v_writelane_b32 v252, s0, 3
	s_cmpk_lt_i32 s78, 0xb00
	s_load_dwordx16 s[8:23], s[80:81], 0x30
	v_writelane_b32 v252, s1, 4
	s_cselect_b64 s[0:1], -1, 0
	v_writelane_b32 v252, s0, 5
	s_ashr_i32 s70, s78, 31
	s_ashr_i32 s71, s82, 31
	v_writelane_b32 v252, s1, 6
	s_lshr_b32 s0, s70, 29
	s_add_i32 s0, s78, s0
	s_ashr_i32 s3, s0, 3
	s_and_b32 s0, s0, -8
	s_sub_i32 s4, s78, s0
	s_cmp_lt_i32 s78, 64
	s_cselect_b64 s[0:1], -1, 0
	v_writelane_b32 v252, s0, 7
	s_cmpk_lt_i32 s78, 0x200
	s_movk_i32 s75, 0x161
	v_writelane_b32 v252, s1, 8
	s_cselect_b64 s[0:1], -1, 0
	s_lshl_b32 s2, s4, 6
	v_writelane_b32 v252, s0, 9
	s_cmpk_lt_i32 s78, 0x780
	v_mov_b32_e32 v149, 0
	v_writelane_b32 v252, s1, 10
	s_cselect_b64 s[0:1], -1, 0
	v_writelane_b32 v252, s0, 11
	s_cmpk_lt_i32 s78, 0x100
	v_mov_b32_e32 v207, 0x358637bd
	v_writelane_b32 v252, s1, 12
	s_cselect_b64 s[0:1], -1, 0
	s_lshl_b32 s5, s4, 5
	s_add_i32 s6, s78, 0xffffff80
	s_cmpk_eq_i32 s82, 0x100
	v_writelane_b32 v252, s0, 13
	s_cselect_b64 s[68:69], -1, 0
	v_mov_b32_e32 v211, 1
	v_writelane_b32 v252, s1, 14
	s_and_b64 s[0:1], s[68:69], exec
	s_cselect_b32 s24, s6, s78
	s_cselect_b32 s72, 0x80, s82
	s_cmpk_lt_u32 s24, 0x110
	s_cselect_b64 s[0:1], -1, 0
	v_writelane_b32 v252, s0, 15
	s_waitcnt lgkmcnt(0)
	s_cmp_lg_u64 s[16:17], 0
	v_mbcnt_hi_u32_b32 v210, -1, v36
	v_writelane_b32 v252, s1, 16
	s_cselect_b64 s[0:1], -1, 0
	v_writelane_b32 v252, s0, 17
	s_cmp_lg_u64 s[12:13], 0
	v_mov_b64_e32 v[250:251], 0x200
	v_writelane_b32 v252, s1, 18
	s_cselect_b64 s[0:1], -1, 0
	v_writelane_b32 v252, s0, 19
	v_mov_b32_e32 v216, 0xff800000
	s_movk_i32 s31, 0x1600
	v_writelane_b32 v252, s1, 20
	v_writelane_b32 v252, s8, 21
	s_cmp_lg_u64 s[8:9], 0
	s_cselect_b64 s[0:1], -1, 0
	v_writelane_b32 v252, s9, 22
	v_writelane_b32 v252, s10, 23
	v_writelane_b32 v252, s11, 24
	v_writelane_b32 v252, s12, 25
	v_writelane_b32 v252, s13, 26
	v_writelane_b32 v252, s14, 27
	v_writelane_b32 v252, s15, 28
	v_writelane_b32 v252, s16, 29
	v_writelane_b32 v252, s17, 30
	v_writelane_b32 v252, s18, 31
	v_writelane_b32 v252, s19, 32
	v_writelane_b32 v252, s20, 33
	v_writelane_b32 v252, s21, 34
	v_writelane_b32 v252, s22, 35
	v_writelane_b32 v252, s23, 36
	v_writelane_b32 v252, s0, 37
	s_cmpk_lt_i32 s78, 0x400
	s_mov_b32 s49, 0
	v_writelane_b32 v252, s1, 38
	s_cselect_b64 s[0:1], -1, 0
	v_writelane_b32 v252, s0, 39
	s_lshr_b32 s73, s78, 3
	s_mov_b64 s[28:29], 0x80
	v_writelane_b32 v252, s1, 40
	s_lshl_b32 s0, s78, 1
	s_and_b32 s0, s0, 14
	s_ashr_i32 s1, s78, 7
	s_add_i32 s74, s0, s1
	s_and_b32 s0, s82, 7
	s_cmp_eq_u32 s0, 0
	s_cselect_b64 s[0:1], -1, 0
	v_writelane_b32 v252, s0, 41
	s_mov_b64 s[36:37], 0x100
	s_nop 0
	v_writelane_b32 v252, s1, 42
	s_lshr_b32 s0, s82, 3
	s_and_b32 s1, s97, 56
	s_mul_i32 s0, s1, s0
	s_add_i32 s0, s0, s78
	s_and_b32 s0, s0, -8
	s_cmp_lt_i32 s4, 0
	v_writelane_b32 v252, s0, 43
	s_mul_i32 s0, s4, 0x41
	s_cselect_b32 s6, s75, 0x160
	s_mul_i32 s1, s4, 33
	s_mul_i32 s6, s4, s6
	s_cselect_b32 s2, s0, s2
	s_movk_i32 s0, 0xf1
	s_cselect_b32 s7, s0, 0xf0
	s_cselect_b32 s1, s1, s5
	s_add_i32 s6, s6, s3
	s_mul_hi_i32 s0, s6, 0x2e8ba2e9
	s_lshr_b32 s5, s0, 31
	s_ashr_i32 s0, s0, 5
	s_add_i32 s0, s0, s5
	s_mul_i32 s5, s0, 0xb0
	s_sub_i32 s5, s6, s5
	s_lshl_b32 s8, s0, 3
	s_bfe_u32 s0, s5, 0x3001c
	s_add_i32 s6, s5, s0
	s_sext_i32_i16 s9, s6
	s_and_b32 s6, s6, 0xfff8
	s_sub_i32 s5, s5, s6
	s_sext_i32_i16 s5, s5
	s_add_i32 s12, s8, s5
	s_ashr_i32 s5, s9, 3
	s_add_i32 s2, s2, s3
	v_writelane_b32 v252, s5, 44
	s_ashr_i32 s5, s2, 31
	s_lshr_b32 s5, s5, 27
	s_add_i32 s5, s2, s5
	s_ashr_i32 s6, s5, 5
	s_and_b32 s5, s5, 0xffe0
	s_sub_i32 s5, s2, s5
	s_bfe_i32 s2, s5, 0x80000
	s_bfe_u32 s2, s2, 0x3000c
	s_add_i32 s8, s5, s2
	s_bfe_i32 s2, s8, 0x80000
	s_and_b32 s8, s8, 0xf8
	s_sub_i32 s5, s5, s8
	s_lshr_b32 s0, s9, 3
	s_lshl_b32 s6, s6, 3
	s_sext_i32_i16 s9, s2
	s_sext_i32_i8 s5, s5
	s_mul_i32 s4, s4, s7
	s_add_i32 s76, s6, s5
	s_ashr_i32 s5, s9, 3
	s_add_i32 s4, s4, s3
	v_writelane_b32 v252, s5, 45
	s_mul_hi_i32 s5, s4, 0x88888889
	s_add_i32 s5, s5, s4
	s_lshr_b32 s6, s5, 31
	s_ashr_i32 s5, s5, 6
	s_add_i32 s5, s5, s6
	s_mul_i32 s6, s5, 0x78
	s_sub_i32 s6, s4, s6
	s_bfe_i32 s4, s6, 0x80000
	s_bfe_u32 s4, s4, 0x3000c
	s_add_i32 s7, s6, s4
	s_bfe_i32 s4, s7, 0x80000
	s_and_b32 s7, s7, 0xf8
	s_sub_i32 s6, s6, s7
	s_lshl_b32 s5, s5, 3
	s_sext_i32_i16 s8, s4
	s_sext_i32_i8 s6, s6
	s_add_i32 s14, s5, s6
	s_ashr_i32 s5, s8, 3
	s_add_i32 s1, s1, s3
	v_writelane_b32 v252, s5, 46
	s_ashr_i32 s5, s1, 31
	s_lshr_b32 s3, s5, 22
	s_add_i32 s3, s1, s3
	s_ashr_i32 s6, s3, 10
	s_lshr_b32 s4, s8, 3
	s_lshl_b32 s8, s6, 3
	s_sub_i32 s6, 2, s8
	s_ashr_i32 s77, s76, 31
	s_lshr_b32 s2, s9, 3
	s_min_u32 s9, s6, 8
	s_lshl_b64 s[6:7], s[76:77], 18
	s_lshr_b32 s5, s5, 28
	v_writelane_b32 v252, s6, 47
	s_add_i32 s5, s1, s5
	s_and_b32 s3, s3, 0xfffffc00
	v_writelane_b32 v252, s7, 48
	s_ashr_i32 s6, s5, 4
	s_and_b32 s5, s5, 0xfff0
	s_sub_i32 s10, s1, s3
	s_sub_i32 s1, s1, s5
	s_bfe_i32 s5, s1, 0x80000
	s_bfe_u32 s5, s5, 0x3000c
	s_add_i32 s5, s1, s5
	s_lshl_b32 s7, s6, 3
	s_bfe_i32 s6, s5, 0x80000
	s_and_b32 s5, s5, 0xf8
	s_sub_i32 s1, s1, s5
	s_sext_i32_i16 s11, s6
	s_sext_i32_i8 s1, s1
	s_add_i32 s18, s7, s1
	s_ashr_i32 s1, s11, 3
	v_writelane_b32 v252, s1, 49
	s_mov_b32 s16, s18
	s_ashr_i32 s19, s18, 31
	v_writelane_b32 v252, s16, 50
	s_lshr_b32 s6, s11, 3
	s_bfe_i64 s[6:7], s[6:7], 0x100000
	v_writelane_b32 v252, s17, 51
	s_lshl_b64 s[16:17], s[18:19], 17
	v_writelane_b32 v252, s16, 52
	s_lshl_b64 s[6:7], s[6:7], 17
	s_ashr_i32 s13, s12, 31
	v_writelane_b32 v252, s17, 53
	v_writelane_b32 v252, s6, 54
	s_bfe_i64 s[0:1], s[0:1], 0x100000
	s_lshl_b64 s[0:1], s[0:1], 19
	v_writelane_b32 v252, s7, 55
	s_mov_b32 s6, s12
	v_writelane_b32 v252, s6, 56
	s_ashr_i32 s15, s14, 31
	s_bfe_i64 s[4:5], s[4:5], 0x100000
	v_writelane_b32 v252, s7, 57
	s_lshl_b64 s[6:7], s[12:13], 19
	v_writelane_b32 v252, s6, 58
	s_bfe_i64 s[2:3], s[2:3], 0x100000
	s_lshl_b64 s[4:5], s[4:5], 19
	v_writelane_b32 v252, s7, 59
	v_writelane_b32 v252, s0, 60
	v_writelane_b32 v253, s4, 0
	v_cvt_f32_ubyte0_e32 v1, s9
	v_writelane_b32 v252, s1, 61
	s_mov_b32 s0, s14
	v_writelane_b32 v252, s0, 62
	v_writelane_b32 v253, s5, 1
	v_cvt_f32_i32_e32 v0, s10
	v_writelane_b32 v252, s1, 63
	s_lshl_b64 s[0:1], s[14:15], 19
	s_add_u32 s0, s90, s0
	s_addc_u32 s1, s91, s1
	s_add_u32 s4, s0, 0x40000
	v_writelane_b32 v253, s0, 2
	s_addc_u32 s5, s1, 0
	v_rcp_iflag_f32_e32 v2, v1
	v_writelane_b32 v253, s1, 3
	v_writelane_b32 v253, s4, 4
	s_lshl_b64 s[0:1], s[2:3], 18
	v_mul_f32_e32 v2, v0, v2
	v_writelane_b32 v253, s5, 5
	v_writelane_b32 v253, s0, 6
	v_trunc_f32_e32 v2, v2
	v_fma_f32 v0, -v2, v1, v0
	v_writelane_b32 v253, s1, 7
	s_lshl_b64 s[0:1], s[2:3], 19
	v_writelane_b32 v253, s0, 8
	s_mov_b64 s[12:13], -1
	s_barrier
	v_readlane_b32 s4, v252, 1
	v_readlane_b32 s5, v252, 2
	v_mov_b32_e32 v4, 0
	s_nop 4
	global_load_dwordx4 v[26:29], v4, s[4:5] sc1
	global_load_dwordx4 v[30:33], v4, s[4:5] offset:16 sc1
	s_waitcnt vmcnt(0)
	v_add_u32_e32 v34, -1, v26
	v_and_b32_e32 v34, v34, v26
	v_mov_b32_e32 v4, v34
	v_min_u32_e32 v34, 1, v26
	v_xor_b32_e32 v34, 1, v34
	v_or_b32_e32 v4, v4, v34
	v_add_u32_e32 v34, -1, v27
	v_and_b32_e32 v34, v34, v27
	v_or_b32_e32 v4, v4, v34
	v_min_u32_e32 v34, 1, v27
	v_xor_b32_e32 v34, 1, v34
	v_or_b32_e32 v4, v4, v34
	v_add_u32_e32 v34, -1, v28
	v_and_b32_e32 v34, v34, v28
	v_or_b32_e32 v4, v4, v34
	v_min_u32_e32 v34, 1, v28
	v_xor_b32_e32 v34, 1, v34
	v_or_b32_e32 v4, v4, v34
	v_add_u32_e32 v34, -1, v29
	v_and_b32_e32 v34, v34, v29
	v_or_b32_e32 v4, v4, v34
	v_min_u32_e32 v34, 1, v29
	v_xor_b32_e32 v34, 1, v34
	v_or_b32_e32 v4, v4, v34
	v_add_u32_e32 v34, -1, v30
	v_and_b32_e32 v34, v34, v30
	v_or_b32_e32 v4, v4, v34
	v_min_u32_e32 v34, 1, v30
	v_xor_b32_e32 v34, 1, v34
	v_or_b32_e32 v4, v4, v34
	v_add_u32_e32 v34, -1, v31
	v_and_b32_e32 v34, v34, v31
	v_or_b32_e32 v4, v4, v34
	v_min_u32_e32 v34, 1, v31
	v_xor_b32_e32 v34, 1, v34
	v_or_b32_e32 v4, v4, v34
	v_add_u32_e32 v34, -1, v32
	v_and_b32_e32 v34, v34, v32
	v_or_b32_e32 v4, v4, v34
	v_min_u32_e32 v34, 1, v32
	v_xor_b32_e32 v34, 1, v34
	v_or_b32_e32 v4, v4, v34
	v_add_u32_e32 v34, -1, v33
	v_and_b32_e32 v34, v34, v33
	v_or_b32_e32 v4, v4, v34
	v_min_u32_e32 v34, 1, v33
	v_xor_b32_e32 v34, 1, v34
	v_or_b32_e32 v4, v4, v34
	v_readfirstlane_b32 s100, v4
	v_writelane_b32 v253, s1, 9
	s_ashr_i32 s0, s10, 30
	s_or_b32 s2, s0, 1
	s_lshl_b64 s[0:1], s[76:77], 19
	v_writelane_b32 v253, s0, 10
	s_nop 1
	v_writelane_b32 v253, s1, 11
	v_cmp_ge_f32_e64 s[0:1], |v0|, v1
	v_cvt_i32_f32_e32 v0, v2
	s_and_b64 s[0:1], s[0:1], exec
	s_cselect_b32 s0, s2, 0
	v_readfirstlane_b32 s1, v0
	s_add_i32 s0, s1, s0
	s_mul_i32 s1, s0, s9
	s_sub_i32 s1, s10, s1
	s_sext_i32_i16 s1, s1
	s_add_i32 s6, s8, s1
	s_ashr_i32 s7, s6, 31
	s_lshl_b64 s[2:3], s[6:7], 19
	v_writelane_b32 v253, s2, 12
	s_mov_b64 s[10:11], 0
	s_nop 0
	v_writelane_b32 v253, s3, 13
	s_bfe_i64 s[2:3], s[0:1], 0x100000
	s_lshl_b64 s[4:5], s[2:3], 19
	s_add_u32 s4, s90, s4
	s_addc_u32 s5, s91, s5
	s_sext_i32_i16 s0, s0
	s_mul_i32 s1, s83, s82
	v_writelane_b32 v253, s0, 14
	s_add_u32 s0, s4, 0x40000
	s_mul_i32 s34, s1, s33
	s_addc_u32 s1, s5, 0
	v_writelane_b32 v253, s0, 15
	s_nop 1
	v_writelane_b32 v253, s1, 16
	s_add_u32 s0, s4, 0x40080
	v_writelane_b32 v253, s4, 17
	s_addc_u32 s1, s5, 0
	s_lshl_b32 s33, s82, 4
	v_writelane_b32 v253, s5, 18
	v_writelane_b32 v253, s0, 19
	s_lshl_b32 s27, s82, 5
	s_nop 0
	v_writelane_b32 v253, s1, 20
	s_lshl_b64 s[0:1], s[2:3], 17
	v_writelane_b32 v253, s0, 21
	s_nop 1
	v_writelane_b32 v253, s1, 22
	s_lshl_b32 s0, s78, 4
	v_writelane_b32 v253, s0, 23
	s_lshl_b32 s0, s78, 5
	v_writelane_b32 v253, s0, 24
	s_lshl_b32 s0, s24, 14
	v_writelane_b32 v253, s0, 25
	s_lshl_b32 s0, s72, 14
	v_writelane_b32 v253, s0, 26
	v_writelane_b32 v253, s24, 27
	s_lshl_b32 s0, s24, 4
	v_writelane_b32 v253, s0, 28
	s_lshl_b32 s0, s72, 4
	v_writelane_b32 v253, s0, 29
	s_mov_b32 s0, s6
	v_writelane_b32 v253, s0, 30
	s_nop 1
	v_writelane_b32 v253, s1, 31
	s_lshl_b64 s[0:1], s[6:7], 17
	v_writelane_b32 v253, s0, 32
	s_nop 1
	v_writelane_b32 v253, s1, 33
	s_add_u32 s0, s86, 0x36c20
	v_writelane_b32 v253, s0, 34
	s_addc_u32 s0, s87, 0
	v_writelane_b32 v253, s0, 35
	s_add_u32 s0, s86, 0x200080
	v_writelane_b32 v253, s0, 36
	s_addc_u32 s0, s87, 0
	v_writelane_b32 v253, s0, 37
	s_lshl_b32 s0, s78, 7
	v_writelane_b32 v253, s0, 38
	s_lshl_b32 s0, s82, 7
	v_writelane_b32 v253, s0, 39
	s_add_u32 s0, s86, 0x7a880
	v_writelane_b32 v253, s0, 40
	s_addc_u32 s0, s87, 0
	v_writelane_b32 v253, s0, 41
	s_add_u32 s0, s78, s82
	s_addc_u32 s1, s70, s71
	v_writelane_b32 v253, s0, 42
	s_ashr_i32 s85, s84, 31
	s_nop 0
	v_writelane_b32 v253, s1, 43
	s_ashr_i32 s0, s97, 31
	v_writelane_b32 v253, s0, 44
	s_lshl_b64 s[0:1], s[84:85], 11
	v_writelane_b32 v253, s0, 45
	s_nop 1
	v_writelane_b32 v253, s1, 46
	s_add_u32 s0, s86, 0x1b600000
	s_addc_u32 s1, s87, 0
	v_writelane_b32 v253, s0, 47
	s_nop 1
	v_writelane_b32 v253, s1, 48
	s_lshl_b64 s[0:1], s[84:85], 10
	v_writelane_b32 v253, s0, 49
	s_nop 1
	v_writelane_b32 v253, s1, 50
	s_add_u32 s0, s86, 0x5600000
	s_addc_u32 s1, s87, 0
	v_writelane_b32 v253, s0, 51
	s_nop 1
	v_writelane_b32 v253, s1, 52
	s_lshl_b32 s0, s78, 8
	v_writelane_b32 v253, s0, 53
	s_lshl_b32 s0, s82, 8
	v_writelane_b32 v253, s0, 54
	s_add_i32 s0, 0, 0x23fc0
	v_writelane_b32 v253, s0, 55
	s_add_i32 s0, 0, 0x23fc4
	v_writelane_b32 v253, s0, 56
	s_add_i32 s0, 0, 0x20100
	v_writelane_b32 v253, s0, 57
	s_add_i32 s0, 0, 0x20900
	v_writelane_b32 v253, s0, 58
	s_load_dwordx2 s[0:1], s[80:81], 0x80
	s_waitcnt lgkmcnt(0)
	v_writelane_b32 v253, s0, 59
	s_nop 1
	v_writelane_b32 v253, s1, 60
	s_load_dwordx4 s[0:3], s[80:81], 0x70
	s_waitcnt lgkmcnt(0)
	v_writelane_b32 v253, s0, 61
	s_nop 1
	v_writelane_b32 v254, s3, 0
	v_writelane_b32 v254, s78, 1
	v_writelane_b32 v254, s80, 2
	s_mov_b32 s0, s82
	v_writelane_b32 v253, s1, 62
	v_writelane_b32 v254, s81, 3
	v_writelane_b32 v254, s0, 4
	v_writelane_b32 v253, s2, 63
	s_nop 0
	v_writelane_b32 v254, s1, 5
	v_writelane_b32 v254, s86, 6
	s_mov_b32 s0, s84
	s_nop 0
	v_writelane_b32 v254, s87, 7
	v_writelane_b32 v254, s97, 8
	v_writelane_b32 v254, s0, 9
	s_nop 1
	v_writelane_b32 v254, s1, 10
	v_writelane_b32 v254, s88, 11
	s_mov_b32 s0, s96
	s_nop 0
	v_writelane_b32 v254, s89, 12
	v_writelane_b32 v254, s90, 13
	s_nop 1
	v_writelane_b32 v254, s91, 14
	v_writelane_b32 v254, s0, 15
	s_nop 1
	v_writelane_b32 v254, s1, 16
	v_writelane_b32 v254, s79, 17
	v_writelane_b32 v254, s92, 18
	s_mov_b32 s0, s76
	s_nop 0
	v_writelane_b32 v254, s93, 19
	v_writelane_b32 v254, s70, 20
	v_writelane_b32 v254, s71, 21
	v_writelane_b32 v254, s68, 22
	s_nop 1
	v_writelane_b32 v254, s69, 23
	v_writelane_b32 v254, s72, 24
	v_writelane_b32 v254, s73, 25
	v_writelane_b32 v254, s74, 26
	v_writelane_b32 v254, s0, 27
	s_nop 1
	v_writelane_b32 v254, s1, 28
	v_writelane_b32 v254, s34, 29
	v_writelane_b32 v254, s33, 30
	v_writelane_b32 v254, s27, 31
	s_branch .LBB0_238
